# ph9 tail as 256 quarter tiles (128x128) on all workgroups
# speedup vs baseline: 1.0060x; 1.0046x over previous
.LBB0_249:
	s_add_i32 s71, s71, 1
	s_mul_i32 s18, s71, s15
	s_mul_hi_u32 s19, s71, s64
	s_add_i32 s19, s19, s18
	s_mul_i32 s18, s71, s64
	s_add_u32 s18, s18, s16
	s_addc_u32 s19, s19, s39
	s_mov_b32 s101, 0
	s_cmp_lg_u32 s71, 1
	s_cbranch_scc1 .Lh9_a
	s_mov_b32 s19, 0
	s_bfe_u32 s101, s16, 0x10001
	s_add_i32 s101, s101, 5
	s_and_b32 s18, s16, 1
	s_lshl_b32 s18, s18, 3
	s_or_b32 s101, s101, s18
	s_lshr_b32 s18, s16, 2
	s_addk_i32 s18, 0x100

.LBB0_251:
	s_ashr_i32 s49, s48, 31
	s_lshl_b64 s[18:19], s[48:49], 19
	s_add_u32 s50, s17, s18
	s_addc_u32 s51, s21, s19
	s_bitcmp0_b32 s101, 1
	s_cbranch_scc1 .Lh9_b
	s_add_u32 s50, s50, 0x40000
	s_addc_u32 s51, s51, 0
.Lh9_b:
	s_ashr_i32 s47, s46, 31
	s_lshl_b64 s[18:19], s[46:47], 19
	s_add_u32 s54, s22, s18
	v_mov_b32_e32 v129, 0
	s_addc_u32 s55, s23, s19
	s_bitcmp0_b32 s101, 3
	s_cbranch_scc1 .Lh9_c
	s_add_u32 s54, s54, 0x40000
	s_addc_u32 s55, s55, 0
.Lh9_c:
	s_andn2_b64 vcc, exec, s[34:35]
	s_cbranch_vccnz .LBB0_255
	s_and_b64 s[18:19], s[42:43], exec
	s_cselect_b32 s47, s51, s57
	s_cselect_b32 s49, s50, s56
	s_cselect_b32 s72, s55, s27
	s_cselect_b32 s73, s54, s26
	s_add_u32 s78, s56, 0x100
	s_addc_u32 s79, s57, 0
	s_add_u32 s80, s26, 0x100
	v_mov_b32_e32 v2, 0
	s_addc_u32 s81, s27, 0
	s_mov_b32 s18, 0
	v_mov_b32_e32 v3, v2
	v_mov_b32_e32 v4, v2
	v_mov_b32_e32 v5, v2
	v_mov_b32_e32 v6, v2
	v_mov_b32_e32 v7, v2
	v_mov_b32_e32 v8, v2
	v_mov_b32_e32 v9, v2
	v_mov_b32_e32 v18, v2
	v_mov_b32_e32 v19, v2
	v_mov_b32_e32 v20, v2
	v_mov_b32_e32 v21, v2
	v_mov_b32_e32 v22, v2
	v_mov_b32_e32 v23, v2
	v_mov_b32_e32 v24, v2
	v_mov_b32_e32 v25, v2
	v_mov_b32_e32 v34, v2
	v_mov_b32_e32 v35, v2
	v_mov_b32_e32 v36, v2
	v_mov_b32_e32 v37, v2
	v_mov_b32_e32 v38, v2
	v_mov_b32_e32 v39, v2
	v_mov_b32_e32 v40, v2
	v_mov_b32_e32 v41, v2
	v_mov_b32_e32 v50, v2
	v_mov_b32_e32 v51, v2
	v_mov_b32_e32 v52, v2
	v_mov_b32_e32 v53, v2
	v_mov_b32_e32 v54, v2
	v_mov_b32_e32 v55, v2
	v_mov_b32_e32 v56, v2
	v_mov_b32_e32 v57, v2
	v_mov_b32_e32 v10, v2
	v_mov_b32_e32 v11, v2
	v_mov_b32_e32 v12, v2
	v_mov_b32_e32 v13, v2
	v_mov_b32_e32 v14, v2
	v_mov_b32_e32 v15, v2
	v_mov_b32_e32 v16, v2
	v_mov_b32_e32 v17, v2
	v_mov_b32_e32 v26, v2
	v_mov_b32_e32 v27, v2
	v_mov_b32_e32 v28, v2
	v_mov_b32_e32 v29, v2
	v_mov_b32_e32 v30, v2
	v_mov_b32_e32 v31, v2
	v_mov_b32_e32 v32, v2
	v_mov_b32_e32 v33, v2
	v_mov_b32_e32 v42, v2
	v_mov_b32_e32 v43, v2
	v_mov_b32_e32 v44, v2
	v_mov_b32_e32 v45, v2
	v_mov_b32_e32 v46, v2
	v_mov_b32_e32 v47, v2
	v_mov_b32_e32 v48, v2
	v_mov_b32_e32 v49, v2
	v_mov_b32_e32 v58, v2
	v_mov_b32_e32 v59, v2
	v_mov_b32_e32 v60, v2
	v_mov_b32_e32 v61, v2
	v_mov_b32_e32 v62, v2
	v_mov_b32_e32 v63, v2
	v_mov_b32_e32 v64, v2
	v_mov_b32_e32 v65, v2
	v_mov_b32_e32 v66, v2
	v_mov_b32_e32 v67, v2
	v_mov_b32_e32 v68, v2
	v_mov_b32_e32 v69, v2
	v_mov_b32_e32 v70, v2
	v_mov_b32_e32 v71, v2
	v_mov_b32_e32 v72, v2
	v_mov_b32_e32 v73, v2
	v_mov_b32_e32 v82, v2
	v_mov_b32_e32 v83, v2
	v_mov_b32_e32 v84, v2
	v_mov_b32_e32 v85, v2
	v_mov_b32_e32 v86, v2
	v_mov_b32_e32 v87, v2
	v_mov_b32_e32 v88, v2
	v_mov_b32_e32 v89, v2
	v_mov_b32_e32 v98, v2
	v_mov_b32_e32 v99, v2
	v_mov_b32_e32 v100, v2
	v_mov_b32_e32 v101, v2
	v_mov_b32_e32 v102, v2
	v_mov_b32_e32 v103, v2
	v_mov_b32_e32 v104, v2
	v_mov_b32_e32 v105, v2
	v_mov_b32_e32 v114, v2
	v_mov_b32_e32 v115, v2
	v_mov_b32_e32 v116, v2
	v_mov_b32_e32 v117, v2
	v_mov_b32_e32 v118, v2
	v_mov_b32_e32 v119, v2
	v_mov_b32_e32 v120, v2
	v_mov_b32_e32 v121, v2
	v_mov_b32_e32 v74, v2
	v_mov_b32_e32 v75, v2
	v_mov_b32_e32 v76, v2
	v_mov_b32_e32 v77, v2
	v_mov_b32_e32 v78, v2
	v_mov_b32_e32 v79, v2
	v_mov_b32_e32 v80, v2
	v_mov_b32_e32 v81, v2
	v_mov_b32_e32 v90, v2
	v_mov_b32_e32 v91, v2
	v_mov_b32_e32 v92, v2
	v_mov_b32_e32 v93, v2
	v_mov_b32_e32 v94, v2
	v_mov_b32_e32 v95, v2
	v_mov_b32_e32 v96, v2
	v_mov_b32_e32 v97, v2
	v_mov_b32_e32 v106, v2
	v_mov_b32_e32 v107, v2
	v_mov_b32_e32 v108, v2
	v_mov_b32_e32 v109, v2
	v_mov_b32_e32 v110, v2
	v_mov_b32_e32 v111, v2
	v_mov_b32_e32 v112, v2
	v_mov_b32_e32 v113, v2
	v_mov_b32_e32 v122, v2
	v_mov_b32_e32 v123, v2
	v_mov_b32_e32 v124, v2
	v_mov_b32_e32 v125, v2
	v_mov_b32_e32 v126, v2
	v_mov_b32_e32 v127, v2
	v_mov_b32_e32 v128, v2
	v_mov_b32_e32 v129, v2
.LBB0_253:
	s_add_i32 s82, s18, 2
	s_cmp_eq_u32 s70, s18
	s_cselect_b32 s18, s49, s78
	s_cselect_b32 s19, s47, s79
	s_cselect_b32 s56, s73, s80
	s_cselect_b32 s57, s72, s81
	s_add_u32 s26, s18, 0x80
	s_addc_u32 s27, s19, 0
	s_add_i32 s83, 0, 0x10000
	v_add_u32_e32 v0, s83, v213
	s_add_i32 s86, 0, 0x14000
	ds_read_b128 v[130:133], v0
	ds_read_b128 v[134:137], v0 offset:1024
	ds_read_b128 v[138:141], v0 offset:2048
	ds_read_b128 v[142:145], v0 offset:3072
	v_add_u32_e32 v0, s86, v213
	ds_read_b128 v[146:149], v0
	ds_read_b128 v[150:153], v0 offset:1024
	ds_read_b128 v[154:157], v0 offset:2048
	ds_read_b128 v[158:161], v0 offset:3072
	s_add_u32 s84, s78, 0x3ff80
	s_addc_u32 s85, s79, 0
	ds_read_b128 v[162:165], v216
	ds_read_b128 v[166:169], v216 offset:1024
	ds_read_b128 v[194:197], v216 offset:2048
	ds_read_b128 v[198:201], v216 offset:3072
	ds_read_b128 v[202:205], v216 offset:4096
	ds_read_b128 v[206:209], v216 offset:5120
	ds_read_b128 v[218:221], v216 offset:6144
	ds_read_b128 v[222:225], v216 offset:7168
	s_add_i32 m0, s40, 0xc000
	v_lshl_add_u64 v[210:211], s[84:85], 0, v[172:173]
	global_load_lds_dwordx4 v[210:211], off
	v_lshl_add_u64 v[210:211], s[84:85], 0, v[170:171]
	s_add_i32 m0, s40, 0xe000
	s_nop 0
	global_load_lds_dwordx4 v[210:211], off
	s_waitcnt vmcnt(8)
	s_waitcnt lgkmcnt(0)
	s_barrier
	s_setprio 1
	s_waitcnt lgkmcnt(0)
	v_mfma_f32_16x16x32_bf16 v[126:129], v[130:133], v[162:165], v[126:129]
	v_mfma_f32_16x16x32_bf16 v[122:125], v[138:141], v[162:165], v[122:125]
	v_mfma_f32_16x16x32_bf16 v[110:113], v[130:133], v[194:197], v[110:113]
	v_mfma_f32_16x16x32_bf16 v[106:109], v[138:141], v[194:197], v[106:109]
	v_mfma_f32_16x16x32_bf16 v[94:97], v[130:133], v[202:205], v[94:97]
	v_mfma_f32_16x16x32_bf16 v[90:93], v[138:141], v[202:205], v[90:93]
	v_mfma_f32_16x16x32_bf16 v[78:81], v[130:133], v[218:221], v[78:81]
	v_mfma_f32_16x16x32_bf16 v[74:77], v[138:141], v[218:221], v[74:77]
	v_mfma_f32_16x16x32_bf16 v[126:129], v[134:137], v[166:169], v[126:129]
	v_mfma_f32_16x16x32_bf16 v[122:125], v[142:145], v[166:169], v[122:125]
	v_mfma_f32_16x16x32_bf16 v[110:113], v[134:137], v[198:201], v[110:113]
	v_mfma_f32_16x16x32_bf16 v[106:109], v[142:145], v[198:201], v[106:109]
	v_mfma_f32_16x16x32_bf16 v[94:97], v[134:137], v[206:209], v[94:97]
	v_mfma_f32_16x16x32_bf16 v[90:93], v[142:145], v[206:209], v[90:93]
	v_mfma_f32_16x16x32_bf16 v[78:81], v[134:137], v[222:225], v[78:81]
	v_mfma_f32_16x16x32_bf16 v[74:77], v[142:145], v[222:225], v[74:77]
	s_bitcmp1_b32 s100, 2
	s_cbranch_scc1 .Lh9_q0
	v_mfma_f32_16x16x32_bf16 v[118:121], v[146:149], v[162:165], v[118:121]
	v_mfma_f32_16x16x32_bf16 v[114:117], v[154:157], v[162:165], v[114:117]
	v_mfma_f32_16x16x32_bf16 v[102:105], v[146:149], v[194:197], v[102:105]
	v_mfma_f32_16x16x32_bf16 v[98:101], v[154:157], v[194:197], v[98:101]
	v_mfma_f32_16x16x32_bf16 v[86:89], v[146:149], v[202:205], v[86:89]
	v_mfma_f32_16x16x32_bf16 v[82:85], v[154:157], v[202:205], v[82:85]
	v_mfma_f32_16x16x32_bf16 v[70:73], v[146:149], v[218:221], v[70:73]
	v_mfma_f32_16x16x32_bf16 v[66:69], v[154:157], v[218:221], v[66:69]
	v_mfma_f32_16x16x32_bf16 v[118:121], v[150:153], v[166:169], v[118:121]
	v_mfma_f32_16x16x32_bf16 v[114:117], v[158:161], v[166:169], v[114:117]
	v_mfma_f32_16x16x32_bf16 v[102:105], v[150:153], v[198:201], v[102:105]
	v_mfma_f32_16x16x32_bf16 v[98:101], v[158:161], v[198:201], v[98:101]
	v_mfma_f32_16x16x32_bf16 v[86:89], v[150:153], v[206:209], v[86:89]
	v_mfma_f32_16x16x32_bf16 v[82:85], v[158:161], v[206:209], v[82:85]
	v_mfma_f32_16x16x32_bf16 v[70:73], v[150:153], v[222:225], v[70:73]
	v_mfma_f32_16x16x32_bf16 v[66:69], v[158:161], v[222:225], v[66:69]
.Lh9_q0:
	s_setprio 0
	s_barrier
	s_mov_b64 s[84:85], s[56:57]
	s_add_i32 s83, s83, s25
	ds_read_b128 v[162:165], v216 offset:16384
	ds_read_b128 v[166:169], v216 offset:17408
	ds_read_b128 v[194:197], v216 offset:18432
	ds_read_b128 v[198:201], v216 offset:19456
	ds_read_b128 v[202:205], v216 offset:20480
	ds_read_b128 v[206:209], v216 offset:21504
	ds_read_b128 v[218:221], v216 offset:22528
	ds_read_b128 v[222:225], v216 offset:23552
	s_mov_b32 m0, s83
	v_lshl_add_u64 v[210:211], s[84:85], 0, v[172:173]
	global_load_lds_dwordx4 v[210:211], off
	s_add_i32 m0, s83, 0x2000
	v_lshl_add_u64 v[210:211], s[84:85], 0, v[170:171]
	s_add_u32 s84, s56, 0x40000
	s_addc_u32 s85, s57, 0
	s_add_i32 s83, s86, s25
	global_load_lds_dwordx4 v[210:211], off
	s_mov_b32 m0, s83
	v_lshl_add_u64 v[210:211], s[84:85], 0, v[172:173]
	global_load_lds_dwordx4 v[210:211], off
	v_lshl_add_u64 v[210:211], s[84:85], 0, v[170:171]
	s_add_i32 m0, s83, 0x2000
	s_mov_b64 s[84:85], s[18:19]
	global_load_lds_dwordx4 v[210:211], off
	s_mov_b32 m0, s40
	v_lshl_add_u64 v[210:211], s[84:85], 0, v[172:173]
	global_load_lds_dwordx4 v[210:211], off
	v_lshl_add_u64 v[210:211], s[84:85], 0, v[170:171]
	s_mov_b32 m0, s41
	s_nop 0
	global_load_lds_dwordx4 v[210:211], off
	s_waitcnt vmcnt(8)
	s_waitcnt lgkmcnt(0)
	s_barrier
	s_setprio 1
	s_waitcnt lgkmcnt(0)
	s_cmp_lg_u32 s100, 0
	s_cbranch_scc1 .Lh9_m0
	v_mfma_f32_16x16x32_bf16 v[62:65], v[130:133], v[162:165], v[62:65]
	v_mfma_f32_16x16x32_bf16 v[58:61], v[138:141], v[162:165], v[58:61]
	v_mfma_f32_16x16x32_bf16 v[46:49], v[130:133], v[194:197], v[46:49]
	v_mfma_f32_16x16x32_bf16 v[42:45], v[138:141], v[194:197], v[42:45]
	v_mfma_f32_16x16x32_bf16 v[30:33], v[130:133], v[202:205], v[30:33]
	v_mfma_f32_16x16x32_bf16 v[26:29], v[138:141], v[202:205], v[26:29]
	v_mfma_f32_16x16x32_bf16 v[14:17], v[130:133], v[218:221], v[14:17]
	v_mfma_f32_16x16x32_bf16 v[10:13], v[138:141], v[218:221], v[10:13]
	v_mfma_f32_16x16x32_bf16 v[62:65], v[134:137], v[166:169], v[62:65]
	v_mfma_f32_16x16x32_bf16 v[58:61], v[142:145], v[166:169], v[58:61]
	v_mfma_f32_16x16x32_bf16 v[46:49], v[134:137], v[198:201], v[46:49]
	v_mfma_f32_16x16x32_bf16 v[42:45], v[142:145], v[198:201], v[42:45]
	v_mfma_f32_16x16x32_bf16 v[30:33], v[134:137], v[206:209], v[30:33]
	v_mfma_f32_16x16x32_bf16 v[26:29], v[142:145], v[206:209], v[26:29]
	v_mfma_f32_16x16x32_bf16 v[14:17], v[134:137], v[222:225], v[14:17]
	v_mfma_f32_16x16x32_bf16 v[10:13], v[142:145], v[222:225], v[10:13]
	v_mfma_f32_16x16x32_bf16 v[54:57], v[146:149], v[162:165], v[54:57]
	v_mfma_f32_16x16x32_bf16 v[50:53], v[154:157], v[162:165], v[50:53]
	v_mfma_f32_16x16x32_bf16 v[38:41], v[146:149], v[194:197], v[38:41]
	v_mfma_f32_16x16x32_bf16 v[34:37], v[154:157], v[194:197], v[34:37]
	v_mfma_f32_16x16x32_bf16 v[22:25], v[146:149], v[202:205], v[22:25]
	v_mfma_f32_16x16x32_bf16 v[18:21], v[154:157], v[202:205], v[18:21]
	v_mfma_f32_16x16x32_bf16 v[6:9], v[146:149], v[218:221], v[6:9]
	v_mfma_f32_16x16x32_bf16 v[2:5], v[154:157], v[218:221], v[2:5]
	v_mfma_f32_16x16x32_bf16 v[54:57], v[150:153], v[166:169], v[54:57]
	v_mfma_f32_16x16x32_bf16 v[50:53], v[158:161], v[166:169], v[50:53]
	v_mfma_f32_16x16x32_bf16 v[38:41], v[150:153], v[198:201], v[38:41]
	v_mfma_f32_16x16x32_bf16 v[34:37], v[158:161], v[198:201], v[34:37]
	v_mfma_f32_16x16x32_bf16 v[22:25], v[150:153], v[206:209], v[22:25]
	v_mfma_f32_16x16x32_bf16 v[18:21], v[158:161], v[206:209], v[18:21]
	v_mfma_f32_16x16x32_bf16 v[6:9], v[150:153], v[222:225], v[6:9]
	v_mfma_f32_16x16x32_bf16 v[2:5], v[158:161], v[222:225], v[2:5]
.Lh9_m0:
	s_setprio 0
	s_barrier
	s_add_i32 s83, 0, 0x18000
	v_add_u32_e32 v0, s83, v213
	s_add_i32 s84, 0, 0x1c000
	ds_read_b128 v[130:133], v0
	ds_read_b128 v[134:137], v0 offset:1024
	ds_read_b128 v[138:141], v0 offset:2048
	ds_read_b128 v[142:145], v0 offset:3072
	v_add_u32_e32 v0, s84, v213
	ds_read_b128 v[146:149], v0
	ds_read_b128 v[150:153], v0 offset:1024
	ds_read_b128 v[154:157], v0 offset:2048
	ds_read_b128 v[158:161], v0 offset:3072
	s_add_u32 s18, s18, 0x40000
	s_addc_u32 s19, s19, 0
	s_mov_b32 m0, s60
	ds_read_b128 v[162:165], v216 offset:32768
	ds_read_b128 v[166:169], v216 offset:33792
	ds_read_b128 v[194:197], v216 offset:34816
	ds_read_b128 v[198:201], v216 offset:35840
	ds_read_b128 v[202:205], v216 offset:36864
	ds_read_b128 v[206:209], v216 offset:37888
	ds_read_b128 v[218:221], v216 offset:38912
	ds_read_b128 v[222:225], v216 offset:39936
	s_nop 0
	v_lshl_add_u64 v[210:211], s[18:19], 0, v[172:173]
	global_load_lds_dwordx4 v[210:211], off
	v_lshl_add_u64 v[210:211], s[18:19], 0, v[170:171]
	s_mov_b32 m0, s61
	s_nop 0
	global_load_lds_dwordx4 v[210:211], off
	s_waitcnt vmcnt(8)
	s_waitcnt lgkmcnt(0)
	s_barrier
	s_setprio 1
	s_waitcnt lgkmcnt(0)
	v_mfma_f32_16x16x32_bf16 v[126:129], v[130:133], v[162:165], v[126:129]
	v_mfma_f32_16x16x32_bf16 v[122:125], v[138:141], v[162:165], v[122:125]
	v_mfma_f32_16x16x32_bf16 v[110:113], v[130:133], v[194:197], v[110:113]
	v_mfma_f32_16x16x32_bf16 v[106:109], v[138:141], v[194:197], v[106:109]
	v_mfma_f32_16x16x32_bf16 v[94:97], v[130:133], v[202:205], v[94:97]
	v_mfma_f32_16x16x32_bf16 v[90:93], v[138:141], v[202:205], v[90:93]
	v_mfma_f32_16x16x32_bf16 v[78:81], v[130:133], v[218:221], v[78:81]
	v_mfma_f32_16x16x32_bf16 v[74:77], v[138:141], v[218:221], v[74:77]
	v_mfma_f32_16x16x32_bf16 v[126:129], v[134:137], v[166:169], v[126:129]
	v_mfma_f32_16x16x32_bf16 v[122:125], v[142:145], v[166:169], v[122:125]
	v_mfma_f32_16x16x32_bf16 v[110:113], v[134:137], v[198:201], v[110:113]
	v_mfma_f32_16x16x32_bf16 v[106:109], v[142:145], v[198:201], v[106:109]
	v_mfma_f32_16x16x32_bf16 v[94:97], v[134:137], v[206:209], v[94:97]
	v_mfma_f32_16x16x32_bf16 v[90:93], v[142:145], v[206:209], v[90:93]
	v_mfma_f32_16x16x32_bf16 v[78:81], v[134:137], v[222:225], v[78:81]
	v_mfma_f32_16x16x32_bf16 v[74:77], v[142:145], v[222:225], v[74:77]
	s_bitcmp1_b32 s100, 2
	s_cbranch_scc1 .Lh9_q1
	v_mfma_f32_16x16x32_bf16 v[118:121], v[146:149], v[162:165], v[118:121]
	v_mfma_f32_16x16x32_bf16 v[114:117], v[154:157], v[162:165], v[114:117]
	v_mfma_f32_16x16x32_bf16 v[102:105], v[146:149], v[194:197], v[102:105]
	v_mfma_f32_16x16x32_bf16 v[98:101], v[154:157], v[194:197], v[98:101]
	v_mfma_f32_16x16x32_bf16 v[86:89], v[146:149], v[202:205], v[86:89]
	v_mfma_f32_16x16x32_bf16 v[82:85], v[154:157], v[202:205], v[82:85]
	v_mfma_f32_16x16x32_bf16 v[70:73], v[146:149], v[218:221], v[70:73]
	v_mfma_f32_16x16x32_bf16 v[66:69], v[154:157], v[218:221], v[66:69]
	v_mfma_f32_16x16x32_bf16 v[118:121], v[150:153], v[166:169], v[118:121]
	v_mfma_f32_16x16x32_bf16 v[114:117], v[158:161], v[166:169], v[114:117]
	v_mfma_f32_16x16x32_bf16 v[102:105], v[150:153], v[198:201], v[102:105]
	v_mfma_f32_16x16x32_bf16 v[98:101], v[158:161], v[198:201], v[98:101]
	v_mfma_f32_16x16x32_bf16 v[86:89], v[150:153], v[206:209], v[86:89]
	v_mfma_f32_16x16x32_bf16 v[82:85], v[158:161], v[206:209], v[82:85]
	v_mfma_f32_16x16x32_bf16 v[70:73], v[150:153], v[222:225], v[70:73]
	v_mfma_f32_16x16x32_bf16 v[66:69], v[158:161], v[222:225], v[66:69]
.Lh9_q1:
	s_setprio 0
	s_barrier
	s_add_u32 s18, s56, 0x80
	s_addc_u32 s19, s57, 0
	s_add_i32 s83, s83, s25
	ds_read_b128 v[162:165], v216 offset:49152
	ds_read_b128 v[166:169], v216 offset:50176
	ds_read_b128 v[194:197], v216 offset:51200
	ds_read_b128 v[198:201], v216 offset:52224
	ds_read_b128 v[202:205], v216 offset:53248
	ds_read_b128 v[206:209], v216 offset:54272
	ds_read_b128 v[218:221], v216 offset:55296
	ds_read_b128 v[222:225], v216 offset:56320
	s_mov_b32 m0, s83
	v_lshl_add_u64 v[210:211], s[18:19], 0, v[172:173]
	global_load_lds_dwordx4 v[210:211], off
	s_add_i32 m0, s83, 0x2000
	v_lshl_add_u64 v[210:211], s[18:19], 0, v[170:171]
	s_add_u32 s18, s56, 0x40080
	s_addc_u32 s19, s57, 0
	s_add_i32 s56, s84, s25
	global_load_lds_dwordx4 v[210:211], off
	s_mov_b32 m0, s56
	v_lshl_add_u64 v[210:211], s[18:19], 0, v[172:173]
	global_load_lds_dwordx4 v[210:211], off
	v_lshl_add_u64 v[210:211], s[18:19], 0, v[170:171]
	s_add_i32 m0, s56, 0x2000
	s_nop 0
	global_load_lds_dwordx4 v[210:211], off
	s_mov_b32 m0, s68
	v_lshl_add_u64 v[210:211], s[26:27], 0, v[172:173]
	global_load_lds_dwordx4 v[210:211], off
	v_lshl_add_u64 v[210:211], s[26:27], 0, v[170:171]
	s_mov_b32 m0, s69
	s_nop 0
	global_load_lds_dwordx4 v[210:211], off
	s_waitcnt vmcnt(8)
	s_waitcnt lgkmcnt(0)
	s_barrier
	s_setprio 1
	s_waitcnt lgkmcnt(0)
	s_cmp_lg_u32 s100, 0
	s_cbranch_scc1 .Lh9_m1
	v_mfma_f32_16x16x32_bf16 v[62:65], v[130:133], v[162:165], v[62:65]
	v_mfma_f32_16x16x32_bf16 v[58:61], v[138:141], v[162:165], v[58:61]
	v_mfma_f32_16x16x32_bf16 v[46:49], v[130:133], v[194:197], v[46:49]
	v_mfma_f32_16x16x32_bf16 v[42:45], v[138:141], v[194:197], v[42:45]
	v_mfma_f32_16x16x32_bf16 v[30:33], v[130:133], v[202:205], v[30:33]
	v_mfma_f32_16x16x32_bf16 v[26:29], v[138:141], v[202:205], v[26:29]
	v_mfma_f32_16x16x32_bf16 v[14:17], v[130:133], v[218:221], v[14:17]
	v_mfma_f32_16x16x32_bf16 v[10:13], v[138:141], v[218:221], v[10:13]
	v_mfma_f32_16x16x32_bf16 v[62:65], v[134:137], v[166:169], v[62:65]
	v_mfma_f32_16x16x32_bf16 v[58:61], v[142:145], v[166:169], v[58:61]
	v_mfma_f32_16x16x32_bf16 v[46:49], v[134:137], v[198:201], v[46:49]
	v_mfma_f32_16x16x32_bf16 v[42:45], v[142:145], v[198:201], v[42:45]
	v_mfma_f32_16x16x32_bf16 v[30:33], v[134:137], v[206:209], v[30:33]
	v_mfma_f32_16x16x32_bf16 v[26:29], v[142:145], v[206:209], v[26:29]
	v_mfma_f32_16x16x32_bf16 v[14:17], v[134:137], v[222:225], v[14:17]
	v_mfma_f32_16x16x32_bf16 v[10:13], v[142:145], v[222:225], v[10:13]
	v_mfma_f32_16x16x32_bf16 v[54:57], v[146:149], v[162:165], v[54:57]
	v_mfma_f32_16x16x32_bf16 v[50:53], v[154:157], v[162:165], v[50:53]
	v_mfma_f32_16x16x32_bf16 v[38:41], v[146:149], v[194:197], v[38:41]
	v_mfma_f32_16x16x32_bf16 v[34:37], v[154:157], v[194:197], v[34:37]
	v_mfma_f32_16x16x32_bf16 v[22:25], v[146:149], v[202:205], v[22:25]
	v_mfma_f32_16x16x32_bf16 v[18:21], v[154:157], v[202:205], v[18:21]
	v_mfma_f32_16x16x32_bf16 v[6:9], v[146:149], v[218:221], v[6:9]
	v_mfma_f32_16x16x32_bf16 v[2:5], v[154:157], v[218:221], v[2:5]
	v_mfma_f32_16x16x32_bf16 v[54:57], v[150:153], v[166:169], v[54:57]
	v_mfma_f32_16x16x32_bf16 v[50:53], v[158:161], v[166:169], v[50:53]
	v_mfma_f32_16x16x32_bf16 v[38:41], v[150:153], v[198:201], v[38:41]
	v_mfma_f32_16x16x32_bf16 v[34:37], v[158:161], v[198:201], v[34:37]
	v_mfma_f32_16x16x32_bf16 v[22:25], v[150:153], v[206:209], v[22:25]
	v_mfma_f32_16x16x32_bf16 v[18:21], v[158:161], v[206:209], v[18:21]
	v_mfma_f32_16x16x32_bf16 v[6:9], v[150:153], v[222:225], v[6:9]
	v_mfma_f32_16x16x32_bf16 v[2:5], v[158:161], v[222:225], v[2:5]

.LBB0_257:
	v_mov_b32_e32 v0, v179
	s_bitcmp1_b32 s100, 1
	s_cselect_b32 vcc_lo, 0x80, 0
	s_bitcmp1_b32 s100, 3
	s_cselect_b32 vcc_hi, 0x80, 0
	s_add_i32 s18, s44, -16
	s_lshr_b32 s18, s18, 3
	v_and_b32_e32 v212, 15, v0
	v_bfe_u32 v214, v0, 4, 2
	v_ashrrev_i32_e32 v130, 2, v0
	v_lshrrev_b32_e32 v0, 1, v0
	s_add_i32 s18, s18, 1
	v_and_b32_e32 v130, 0xffffffc0, v130
	v_and_b32_e32 v0, 0x60, v0
	s_cmp_gt_i32 s44, 15
	v_lshl_add_u32 v146, s44, 8, v130
	v_add_u32_e32 v146, vcc_lo, v146
	v_lshl_or_b32 v0, s45, 8, v0
	v_add_u32_e32 v0, vcc_hi, v0
	s_cselect_b32 s18, s18, 0
	v_lshl_or_b32 v130, v214, 2, v0
	s_mul_hi_u32 s19, s18, 0x6000
	s_mulk_i32 s18, 0x6000
	v_or_b32_e32 v210, v146, v212
	s_add_u32 s18, s62, s18
	v_ashrrev_i32_e32 v131, 31, v130
	v_lshlrev_b32_e32 v0, 4, v214
	v_ashrrev_i32_e32 v211, 31, v210
	s_addc_u32 s19, s63, s19
	v_lshlrev_b64 v[194:195], 2, v[130:131]
	v_lshl_add_u64 v[146:147], s[30:31], 0, v[0:1]
	v_lshlrev_b64 v[148:149], 6, v[210:211]
	v_or_b32_e32 v208, 16, v210
	v_lshl_add_u64 v[130:131], s[18:19], 0, v[194:195]
	v_lshl_add_u64 v[148:149], v[146:147], 0, v[148:149]
	v_ashrrev_i32_e32 v209, 31, v208
	global_load_dwordx4 v[142:145], v[130:131], off
	global_load_dwordx4 v[138:141], v[130:131], off offset:64
	global_load_dwordx4 v[134:137], v[130:131], off offset:512
	s_nop 0
	global_load_dwordx4 v[130:133], v[130:131], off offset:576
	v_or_b32_e32 v206, 32, v210
	global_load_dwordx4 v[220:223], v[148:149], off
	v_lshlrev_b64 v[148:149], 6, v[208:209]
	v_lshl_add_u64 v[148:149], v[146:147], 0, v[148:149]
	global_load_dwordx4 v[224:227], v[148:149], off
	v_ashrrev_i32_e32 v207, 31, v206
	v_lshlrev_b64 v[148:149], 6, v[206:207]
	v_or_b32_e32 v204, 48, v210
	v_lshl_add_u64 v[148:149], v[146:147], 0, v[148:149]
	v_ashrrev_i32_e32 v205, 31, v204
	global_load_dwordx4 v[166:169], v[148:149], off
	v_lshlrev_b64 v[148:149], 6, v[204:205]
	v_lshl_add_u64 v[148:149], v[146:147], 0, v[148:149]
	global_load_dwordx4 v[162:165], v[148:149], off
	v_add_u32_e32 v202, 0x80, v210
	v_ashrrev_i32_e32 v203, 31, v202
	v_lshlrev_b64 v[148:149], 6, v[202:203]
	v_add_u32_e32 v200, 0x90, v210
	v_lshl_add_u64 v[148:149], v[146:147], 0, v[148:149]
	v_ashrrev_i32_e32 v201, 31, v200
	global_load_dwordx4 v[158:161], v[148:149], off
	v_lshlrev_b64 v[148:149], 6, v[200:201]
	v_lshl_add_u64 v[148:149], v[146:147], 0, v[148:149]
	global_load_dwordx4 v[154:157], v[148:149], off
	v_add_u32_e32 v198, 0xa0, v210
	v_ashrrev_i32_e32 v199, 31, v198
	v_lshlrev_b64 v[148:149], 6, v[198:199]
	v_add_u32_e32 v196, 0xb0, v210
	v_lshl_add_u64 v[148:149], v[146:147], 0, v[148:149]
	v_ashrrev_i32_e32 v197, 31, v196
	global_load_dwordx4 v[150:153], v[148:149], off
	v_lshlrev_b64 v[148:149], 6, v[196:197]
	v_lshl_add_u64 v[146:147], v[146:147], 0, v[148:149]
	global_load_dwordx4 v[146:149], v[146:147], off
	v_lshlrev_b32_e32 v0, 6, v214
	v_lshlrev_b32_e32 v212, 2, v212
	v_bitop3_b32 v218, v0, 64, v212 bitop3:0x36
	v_bitop3_b32 v217, v0, s90, v212 bitop3:0x36
	s_mov_b32 s18, 0x358637bd
	s_waitcnt vmcnt(0)
	v_mov_b32_e32 v214, v221
	v_mov_b32_e32 v215, v222
	v_mov_b32_e32 v221, v223
	v_pk_add_f32 v[214:215], v[214:215], v[220:221]
	v_mov_b32_e32 v220, v225
	v_mov_b32_e32 v221, v226
	v_mov_b32_e32 v225, v227
	v_pk_add_f32 v[220:221], v[220:221], v[224:225]
	v_mov_b32_e32 v223, v214
	v_mov_b32_e32 v222, v220
	v_mov_b32_e32 v214, v221
	v_pk_add_f32 v[214:215], v[222:223], v[214:215]
	ds_bpermute_b32 v221, v218, v215
	ds_bpermute_b32 v220, v218, v214
	s_waitcnt lgkmcnt(0)
	v_pk_add_f32 v[214:215], v[214:215], v[220:221]
	ds_bpermute_b32 v221, v217, v215
	ds_bpermute_b32 v220, v217, v214
	s_waitcnt lgkmcnt(0)
	v_pk_add_f32 v[220:221], v[214:215], v[220:221]
	v_mov_b64_e32 v[214:215], s[18:19]
	v_pk_fma_f32 v[220:221], v[220:221], s[38:39], v[214:215] op_sel_hi:[1,0,0]
	s_mov_b64 s[18:19], -1
	v_mul_f32_e32 v0, 0x4b800000, v221
	v_cmp_gt_f32_e64 s[44:45], s20, v221
	v_cmp_gt_f32_e32 vcc, s20, v220
	s_nop 0
	v_cndmask_b32_e64 v0, v221, v0, s[44:45]
	v_rsq_f32_e32 v0, v0
	v_mov_b32_e32 v221, v168
	v_mov_b32_e32 v168, v163
	v_mov_b32_e32 v163, v165
	v_mul_f32_e32 v212, 0x45800000, v0
	v_cndmask_b32_e64 v212, v0, v212, s[44:45]
	v_mul_f32_e32 v0, 0x4b800000, v220
	v_cndmask_b32_e32 v0, v220, v0, vcc
	v_mov_b32_e32 v220, v167
	v_mov_b32_e32 v167, v169
	v_mov_b32_e32 v169, v164
	v_pk_add_f32 v[166:167], v[220:221], v[166:167]
	v_pk_add_f32 v[162:163], v[168:169], v[162:163]
	v_mov_b32_e32 v165, v166
	v_mov_b32_e32 v164, v162
	v_mov_b32_e32 v166, v163
	v_pk_add_f32 v[162:163], v[164:165], v[166:167]
	ds_bpermute_b32 v165, v218, v163
	ds_bpermute_b32 v164, v218, v162
	v_mov_b32_e32 v166, v159
	v_mov_b32_e32 v167, v160
	v_mov_b32_e32 v159, v161
	v_mov_b32_e32 v160, v155
	v_mov_b32_e32 v161, v156
	v_mov_b32_e32 v155, v157
	v_pk_add_f32 v[158:159], v[166:167], v[158:159]
	v_pk_add_f32 v[154:155], v[160:161], v[154:155]
	s_waitcnt lgkmcnt(0)
	v_pk_add_f32 v[162:163], v[162:163], v[164:165]
	v_mov_b32_e32 v156, v154
	v_mov_b32_e32 v157, v158
	v_mov_b32_e32 v158, v155
	ds_bpermute_b32 v165, v217, v163
	ds_bpermute_b32 v164, v217, v162
	v_pk_add_f32 v[154:155], v[156:157], v[158:159]
	ds_bpermute_b32 v157, v218, v155
	ds_bpermute_b32 v156, v218, v154
	v_mov_b32_e32 v158, v151
	v_mov_b32_e32 v159, v152
	v_mov_b32_e32 v151, v153
	v_mov_b32_e32 v152, v147
	v_mov_b32_e32 v153, v148
	v_mov_b32_e32 v147, v149
	s_waitcnt lgkmcnt(2)
	v_pk_add_f32 v[162:163], v[162:163], v[164:165]
	v_pk_add_f32 v[150:151], v[158:159], v[150:151]
	v_pk_add_f32 v[146:147], v[152:153], v[146:147]
	v_pk_fma_f32 v[162:163], v[162:163], s[38:39], v[214:215] op_sel_hi:[1,0,0]
	s_waitcnt lgkmcnt(0)
	v_pk_add_f32 v[154:155], v[154:155], v[156:157]
	v_mov_b32_e32 v148, v146
	v_mov_b32_e32 v149, v150
	v_mov_b32_e32 v150, v147
	v_mul_f32_e32 v164, 0x4b800000, v163
	v_cmp_gt_f32_e64 s[44:45], s20, v163
	ds_bpermute_b32 v157, v217, v155
	ds_bpermute_b32 v156, v217, v154
	v_pk_add_f32 v[146:147], v[148:149], v[150:151]
	v_cndmask_b32_e64 v163, v163, v164, s[44:45]
	ds_bpermute_b32 v149, v218, v147
	ds_bpermute_b32 v148, v218, v146
	v_rsq_f32_e32 v0, v0
	v_rsq_f32_e32 v163, v163
	s_waitcnt lgkmcnt(2)
	v_pk_add_f32 v[154:155], v[154:155], v[156:157]
	v_lshlrev_b64 v[150:151], 12, v[210:211]
	v_mul_f32_e32 v219, 0x45800000, v0
	v_mul_f32_e32 v164, 0x45800000, v163
	v_pk_fma_f32 v[154:155], v[154:155], s[38:39], v[214:215] op_sel_hi:[1,0,0]
	s_waitcnt lgkmcnt(0)
	v_pk_add_f32 v[146:147], v[146:147], v[148:149]
	v_cndmask_b32_e32 v0, v0, v219, vcc
	v_cmp_gt_f32_e32 vcc, s20, v162
	v_cndmask_b32_e64 v164, v163, v164, s[44:45]
	v_mul_f32_e32 v163, 0x4b800000, v162
	v_mul_f32_e32 v156, 0x4b800000, v155
	v_cmp_gt_f32_e64 s[44:45], s20, v155
	ds_bpermute_b32 v149, v217, v147
	ds_bpermute_b32 v148, v217, v146
	v_lshl_add_u64 v[150:151], s[2:3], 0, v[150:151]
	v_cndmask_b32_e32 v162, v162, v163, vcc
	v_cndmask_b32_e64 v155, v155, v156, s[44:45]
	v_lshl_add_u64 v[150:151], v[150:151], 0, v[194:195]
	v_pk_fma_f32 v[116:117], v[116:117], v[212:213], v[132:133] op_sel_hi:[1,0,1]
	v_pk_fma_f32 v[114:115], v[114:115], v[212:213], v[130:131] op_sel_hi:[1,0,1]
	v_rsq_f32_e32 v162, v162
	v_rsq_f32_e32 v155, v155
	s_bitcmp1_b32 s100, 2
	s_cbranch_scc1 .Lh9_t0
	global_store_dwordx4 v[150:151], v[114:117], off offset:576
.Lh9_t0:
	v_pk_fma_f32 v[100:101], v[100:101], v[0:1], v[132:133] op_sel_hi:[1,0,1]
	v_pk_fma_f32 v[98:99], v[98:99], v[0:1], v[130:131] op_sel_hi:[1,0,1]
	v_lshlrev_b64 v[114:115], 12, v[208:209]
	v_lshl_add_u64 v[114:115], s[2:3], 0, v[114:115]
	v_lshl_add_u64 v[114:115], v[114:115], 0, v[194:195]
	s_waitcnt lgkmcnt(0)
	v_pk_add_f32 v[146:147], v[146:147], v[148:149]
	s_bitcmp1_b32 s100, 2
	s_cbranch_scc1 .Lh9_t1
	global_store_dwordx4 v[114:115], v[98:101], off offset:576
.Lh9_t1:
	v_mul_f32_e32 v163, 0x45800000, v162
	v_mul_f32_e32 v156, 0x45800000, v155
	v_lshlrev_b64 v[98:99], 12, v[206:207]
	v_pk_fma_f32 v[146:147], v[146:147], s[38:39], v[214:215] op_sel_hi:[1,0,0]
	v_lshl_add_u64 v[98:99], s[2:3], 0, v[98:99]
	v_cndmask_b32_e32 v162, v162, v163, vcc
	v_cmp_gt_f32_e32 vcc, s20, v154
	v_cndmask_b32_e64 v156, v155, v156, s[44:45]
	v_mul_f32_e32 v155, 0x4b800000, v154
	v_mul_f32_e32 v148, 0x4b800000, v147
	v_cmp_gt_f32_e64 s[44:45], s20, v147
	v_lshl_add_u64 v[98:99], v[98:99], 0, v[194:195]
	v_pk_fma_f32 v[84:85], v[84:85], v[164:165], v[132:133] op_sel_hi:[1,0,1]
	v_pk_fma_f32 v[82:83], v[82:83], v[164:165], v[130:131] op_sel_hi:[1,0,1]
	v_cndmask_b32_e32 v154, v154, v155, vcc
	v_cndmask_b32_e64 v147, v147, v148, s[44:45]
	s_bitcmp1_b32 s100, 2
	s_cbranch_scc1 .Lh9_t2
	global_store_dwordx4 v[98:99], v[82:85], off offset:576
.Lh9_t2:
	v_rsq_f32_e32 v154, v154
	v_rsq_f32_e32 v147, v147
	v_lshlrev_b64 v[82:83], 12, v[204:205]
	v_lshl_add_u64 v[82:83], s[2:3], 0, v[82:83]
	v_lshl_add_u64 v[82:83], v[82:83], 0, v[194:195]
	v_pk_fma_f32 v[68:69], v[68:69], v[162:163], v[132:133] op_sel_hi:[1,0,1]
	v_pk_fma_f32 v[66:67], v[66:67], v[162:163], v[130:131] op_sel_hi:[1,0,1]
	s_bitcmp1_b32 s100, 2
	s_cbranch_scc1 .Lh9_t3
	global_store_dwordx4 v[82:83], v[66:69], off offset:576
.Lh9_t3:
	v_mul_f32_e32 v155, 0x45800000, v154
	v_mul_f32_e32 v148, 0x45800000, v147
	v_lshlrev_b64 v[66:67], 12, v[202:203]
	v_lshl_add_u64 v[66:67], s[2:3], 0, v[66:67]
	v_lshl_add_u64 v[66:67], v[66:67], 0, v[194:195]
	v_pk_fma_f32 v[52:53], v[52:53], v[156:157], v[132:133] op_sel_hi:[1,0,1]
	v_pk_fma_f32 v[50:51], v[50:51], v[156:157], v[130:131] op_sel_hi:[1,0,1]
	v_cndmask_b32_e32 v154, v154, v155, vcc
	v_cmp_gt_f32_e32 vcc, s20, v146
	v_cndmask_b32_e64 v148, v147, v148, s[44:45]
	v_mul_f32_e32 v147, 0x4b800000, v146
	s_cmp_lg_u32 s100, 0
	s_cbranch_scc1 .Lh9_s0
	global_store_dwordx4 v[66:67], v[50:53], off offset:576

.Lh9_s2:
	v_cndmask_b32_e32 v146, v146, v147, vcc
	v_pk_fma_f32 v[128:129], v[128:129], v[212:213], v[144:145] op_sel_hi:[1,0,1]
	v_lshlrev_b64 v[18:19], 12, v[196:197]
	v_lshl_add_u64 v[18:19], s[2:3], 0, v[18:19]
	v_pk_fma_f32 v[126:127], v[126:127], v[212:213], v[142:143] op_sel_hi:[1,0,1]
	v_pk_fma_f32 v[124:125], v[124:125], v[212:213], v[140:141] op_sel_hi:[1,0,1]
	v_pk_fma_f32 v[122:123], v[122:123], v[212:213], v[138:139] op_sel_hi:[1,0,1]
	v_pk_fma_f32 v[120:121], v[120:121], v[212:213], v[136:137] op_sel_hi:[1,0,1]
	v_pk_fma_f32 v[118:119], v[118:119], v[212:213], v[134:135] op_sel_hi:[1,0,1]
	v_pk_fma_f32 v[112:113], v[112:113], v[0:1], v[144:145] op_sel_hi:[1,0,1]
	v_pk_fma_f32 v[110:111], v[110:111], v[0:1], v[142:143] op_sel_hi:[1,0,1]
	v_pk_fma_f32 v[108:109], v[108:109], v[0:1], v[140:141] op_sel_hi:[1,0,1]
	v_pk_fma_f32 v[106:107], v[106:107], v[0:1], v[138:139] op_sel_hi:[1,0,1]
	v_pk_fma_f32 v[104:105], v[104:105], v[0:1], v[136:137] op_sel_hi:[1,0,1]
	v_pk_fma_f32 v[102:103], v[102:103], v[0:1], v[134:135] op_sel_hi:[1,0,1]
	v_pk_fma_f32 v[96:97], v[96:97], v[164:165], v[144:145] op_sel_hi:[1,0,1]
	v_pk_fma_f32 v[94:95], v[94:95], v[164:165], v[142:143] op_sel_hi:[1,0,1]
	v_pk_fma_f32 v[92:93], v[92:93], v[164:165], v[140:141] op_sel_hi:[1,0,1]
	v_pk_fma_f32 v[90:91], v[90:91], v[164:165], v[138:139] op_sel_hi:[1,0,1]
	v_pk_fma_f32 v[88:89], v[88:89], v[164:165], v[136:137] op_sel_hi:[1,0,1]
	v_pk_fma_f32 v[86:87], v[86:87], v[164:165], v[134:135] op_sel_hi:[1,0,1]
	v_pk_fma_f32 v[80:81], v[80:81], v[162:163], v[144:145] op_sel_hi:[1,0,1]
	v_pk_fma_f32 v[78:79], v[78:79], v[162:163], v[142:143] op_sel_hi:[1,0,1]
	v_pk_fma_f32 v[76:77], v[76:77], v[162:163], v[140:141] op_sel_hi:[1,0,1]
	v_pk_fma_f32 v[74:75], v[74:75], v[162:163], v[138:139] op_sel_hi:[1,0,1]
	v_pk_fma_f32 v[72:73], v[72:73], v[162:163], v[136:137] op_sel_hi:[1,0,1]
	v_pk_fma_f32 v[70:71], v[70:71], v[162:163], v[134:135] op_sel_hi:[1,0,1]
	v_pk_fma_f32 v[64:65], v[64:65], v[156:157], v[144:145] op_sel_hi:[1,0,1]
	v_pk_fma_f32 v[62:63], v[62:63], v[156:157], v[142:143] op_sel_hi:[1,0,1]
	v_pk_fma_f32 v[60:61], v[60:61], v[156:157], v[140:141] op_sel_hi:[1,0,1]
	v_pk_fma_f32 v[58:59], v[58:59], v[156:157], v[138:139] op_sel_hi:[1,0,1]
	v_pk_fma_f32 v[56:57], v[56:57], v[156:157], v[136:137] op_sel_hi:[1,0,1]
	v_pk_fma_f32 v[54:55], v[54:55], v[156:157], v[134:135] op_sel_hi:[1,0,1]
	v_pk_fma_f32 v[48:49], v[48:49], v[154:155], v[144:145] op_sel_hi:[1,0,1]
	v_pk_fma_f32 v[46:47], v[46:47], v[154:155], v[142:143] op_sel_hi:[1,0,1]
	v_pk_fma_f32 v[44:45], v[44:45], v[154:155], v[140:141] op_sel_hi:[1,0,1]
	v_pk_fma_f32 v[42:43], v[42:43], v[154:155], v[138:139] op_sel_hi:[1,0,1]
	v_pk_fma_f32 v[40:41], v[40:41], v[154:155], v[136:137] op_sel_hi:[1,0,1]
	v_pk_fma_f32 v[38:39], v[38:39], v[154:155], v[134:135] op_sel_hi:[1,0,1]
	v_pk_fma_f32 v[32:33], v[32:33], v[148:149], v[144:145] op_sel_hi:[1,0,1]
	v_pk_fma_f32 v[30:31], v[30:31], v[148:149], v[142:143] op_sel_hi:[1,0,1]
	v_pk_fma_f32 v[28:29], v[28:29], v[148:149], v[140:141] op_sel_hi:[1,0,1]
	v_pk_fma_f32 v[26:27], v[26:27], v[148:149], v[138:139] op_sel_hi:[1,0,1]
	v_pk_fma_f32 v[24:25], v[24:25], v[148:149], v[136:137] op_sel_hi:[1,0,1]
	v_pk_fma_f32 v[22:23], v[22:23], v[148:149], v[134:135] op_sel_hi:[1,0,1]
	v_lshl_add_u64 v[18:19], v[18:19], 0, v[194:195]
	v_pk_fma_f32 v[16:17], v[16:17], v[146:147], v[144:145] op_sel_hi:[1,0,1]
	v_pk_fma_f32 v[14:15], v[14:15], v[146:147], v[142:143] op_sel_hi:[1,0,1]
	v_pk_fma_f32 v[12:13], v[12:13], v[146:147], v[140:141] op_sel_hi:[1,0,1]
	v_pk_fma_f32 v[10:11], v[10:11], v[146:147], v[138:139] op_sel_hi:[1,0,1]
	v_pk_fma_f32 v[8:9], v[8:9], v[146:147], v[136:137] op_sel_hi:[1,0,1]
	v_pk_fma_f32 v[6:7], v[6:7], v[146:147], v[134:135] op_sel_hi:[1,0,1]
	v_pk_fma_f32 v[4:5], v[4:5], v[146:147], v[132:133] op_sel_hi:[1,0,1]
	v_pk_fma_f32 v[2:3], v[2:3], v[146:147], v[130:131] op_sel_hi:[1,0,1]
	s_andn2_b64 vcc, exec, s[42:43]
	global_store_dwordx4 v[150:151], v[126:129], off
	global_store_dwordx4 v[150:151], v[122:125], off offset:64
	s_bitcmp1_b32 s100, 2
	s_cbranch_scc1 .Lh9_t4
	global_store_dwordx4 v[150:151], v[118:121], off offset:512
.Lh9_t4:
	global_store_dwordx4 v[114:115], v[110:113], off
	global_store_dwordx4 v[114:115], v[106:109], off offset:64
	s_bitcmp1_b32 s100, 2
	s_cbranch_scc1 .Lh9_t5
	global_store_dwordx4 v[114:115], v[102:105], off offset:512
.Lh9_t5:
	global_store_dwordx4 v[98:99], v[94:97], off
	global_store_dwordx4 v[98:99], v[90:93], off offset:64
	s_bitcmp1_b32 s100, 2
	s_cbranch_scc1 .Lh9_t6
	global_store_dwordx4 v[98:99], v[86:89], off offset:512
.Lh9_t6:
	global_store_dwordx4 v[82:83], v[78:81], off
	global_store_dwordx4 v[82:83], v[74:77], off offset:64
	s_bitcmp1_b32 s100, 2
	s_cbranch_scc1 .Lh9_t7
	global_store_dwordx4 v[82:83], v[70:73], off offset:512
.Lh9_t7:
	s_cmp_lg_u32 s100, 0
	s_cbranch_scc1 .Lh9_e
	global_store_dwordx4 v[66:67], v[62:65], off
	global_store_dwordx4 v[66:67], v[58:61], off offset:64
	global_store_dwordx4 v[66:67], v[54:57], off offset:512
	global_store_dwordx4 v[50:51], v[46:49], off
	global_store_dwordx4 v[50:51], v[42:45], off offset:64
	global_store_dwordx4 v[50:51], v[38:41], off offset:512
	global_store_dwordx4 v[34:35], v[30:33], off
	global_store_dwordx4 v[34:35], v[26:29], off offset:64
	global_store_dwordx4 v[34:35], v[22:25], off offset:512
	global_store_dwordx4 v[18:19], v[14:17], off
	global_store_dwordx4 v[18:19], v[10:13], off offset:64
	global_store_dwordx4 v[18:19], v[6:9], off offset:512
	global_store_dwordx4 v[18:19], v[2:5], off offset:576
